# pk4 + grid-barrier / flag poll loops without the 64-cycle sleep (s_sleep 0, 25 sites)
# speedup vs baseline: 1.0148x; 1.0065x over previous
.LBB0_335:
	v_mov_b64_e32 v[14:15], s[34:35]
	flat_load_dword v12, v[14:15] offset:1024 sc1
	s_waitcnt lgkmcnt(0)
	flat_load_dword v0, v[14:15] offset:1280 sc1
	flat_load_dword v2, v[14:15] offset:1536 sc1
	flat_load_dword v3, v[14:15] offset:1792 sc1
	flat_load_dword v4, v[14:15] offset:2048 sc1
	flat_load_dword v5, v[14:15] offset:2304 sc1
	flat_load_dword v6, v[14:15] offset:2560 sc1
	flat_load_dword v7, v[14:15] offset:2816 sc1
	flat_load_dword v8, v[14:15] offset:3072 sc1
	flat_load_dword v9, v[14:15] offset:3328 sc1
	flat_load_dword v10, v[14:15] offset:3584 sc1
	flat_load_dword v11, v[14:15] offset:3840 sc1
	v_mov_b64_e32 v[14:15], s[0:1]
	flat_load_dword v13, v[14:15] sc1
	v_mov_b64_e32 v[14:15], s[4:5]
	flat_load_dword v14, v[14:15] sc1
	v_mov_b64_e32 v[16:17], s[6:7]
	flat_load_dword v15, v[16:17] sc1
	v_mov_b64_e32 v[16:17], s[8:9]
	flat_load_dword v16, v[16:17] sc1
	v_readlane_b32 s18, v254, 12
	s_or_b64 s[16:17], s[16:17], exec
	s_or_b64 s[14:15], s[14:15], exec
	s_waitcnt vmcnt(0) lgkmcnt(0)
	v_add_u32_e32 v17, v0, v12
	v_add_u32_e32 v17, v17, v2
	v_add_u32_e32 v17, v17, v3
	v_add_u32_e32 v17, v17, v4
	v_add_u32_e32 v17, v17, v5
	v_add_u32_e32 v17, v17, v6
	v_add_u32_e32 v17, v17, v7
	v_add_u32_e32 v17, v17, v8
	v_add_u32_e32 v17, v17, v9
	v_add_u32_e32 v17, v17, v10
	v_add_u32_e32 v17, v17, v11
	v_add_u32_e32 v17, v17, v13
	v_add_u32_e32 v17, v17, v14
	v_add_u32_e32 v17, v17, v15
	v_add_u32_e32 v17, v17, v16
	v_cmp_ne_u32_e32 vcc, s18, v17
	s_and_saveexec_b64 s[18:19], vcc
	s_cbranch_execz .LBB0_334
	s_and_b32 s22, s28, 0xff
	s_mov_b64 s[20:21], -1
	s_cmp_eq_u32 s22, 0
	s_mov_b64 s[24:25], -1
	s_mov_b64 s[22:23], -1
	s_sleep 0
	s_cbranch_scc1 .LBB0_338
	s_and_saveexec_b64 s[26:27], s[24:25]
	s_cbranch_execz .LBB0_333
	s_branch .LBB0_341

.LBB0_349:
	s_and_b32 s16, s23, 0xff
	s_mov_b64 s[14:15], -1
	s_cmp_lg_u32 s16, 0
	s_mov_b64 s[16:17], -1
	s_sleep 0
	s_cbranch_scc1 .LBB0_353
	v_mov_b64_e32 v[4:5], s[34:35]
	flat_load_dword v0, v[4:5] offset:512 sc1
	s_mov_b64 s[16:17], 0
	s_mov_b64 s[18:19], -1
	s_waitcnt vmcnt(0) lgkmcnt(0)
	v_cmp_eq_u32_e32 vcc, 0, v0
	s_and_saveexec_b64 s[20:21], vcc
	s_cmp_lt_u32 s23, 0x40001
	s_cselect_b64 s[16:17], -1, 0
	s_xor_b64 s[18:19], exec, -1
	s_and_b64 s[16:17], s[16:17], exec
	s_or_b64 exec, exec, s[20:21]

.LBB0_363:
	s_and_b32 s16, s23, 0xff
	s_mov_b64 s[14:15], -1
	s_cmp_lg_u32 s16, 0
	s_mov_b64 s[18:19], -1
	s_sleep 0
	s_cbranch_scc0 .LBB0_365
	s_and_saveexec_b64 s[20:21], s[18:19]
	s_cbranch_execz .LBB0_362
	s_branch .LBB0_368

.LBB0_383:
	s_sleep 0
	global_load_dword v2, v1, s[2:3] offset:32 sc1
	s_waitcnt vmcnt(0)
	v_and_b32_e32 v2, 0xffff0000, v2
	v_cmp_ne_u32_e32 vcc, v2, v0
	s_or_b64 s[4:5], vcc, s[4:5]
	s_andn2_b64 exec, exec, s[4:5]
	s_cbranch_execnz .LBB0_383

.LBB0_529:
	v_mov_b64_e32 v[12:13], s[34:35]
	flat_load_dword v2, v[12:13] offset:1024 sc1
	s_waitcnt lgkmcnt(0)
	flat_load_dword v0, v[12:13] offset:1280 sc1
	flat_load_dword v3, v[12:13] offset:1536 sc1
	flat_load_dword v4, v[12:13] offset:1792 sc1
	flat_load_dword v5, v[12:13] offset:2048 sc1
	flat_load_dword v6, v[12:13] offset:2304 sc1
	flat_load_dword v7, v[12:13] offset:2560 sc1
	flat_load_dword v8, v[12:13] offset:2816 sc1
	flat_load_dword v9, v[12:13] offset:3072 sc1
	flat_load_dword v10, v[12:13] offset:3328 sc1
	flat_load_dword v11, v[12:13] offset:3584 sc1
	s_nop 0
	flat_load_dword v12, v[12:13] offset:3840 sc1
	v_mov_b64_e32 v[14:15], s[0:1]
	flat_load_dword v13, v[14:15] sc1
	v_mov_b64_e32 v[14:15], s[4:5]
	flat_load_dword v14, v[14:15] sc1
	v_mov_b64_e32 v[16:17], s[6:7]
	flat_load_dword v15, v[16:17] sc1
	v_mov_b64_e32 v[16:17], s[8:9]
	flat_load_dword v16, v[16:17] sc1
	v_readlane_b32 s18, v254, 12
	s_or_b64 s[16:17], s[16:17], exec
	s_or_b64 s[14:15], s[14:15], exec
	s_waitcnt vmcnt(0) lgkmcnt(0)
	v_add_u32_e32 v17, v0, v2
	v_add_u32_e32 v17, v17, v3
	v_add_u32_e32 v17, v17, v4
	v_add_u32_e32 v17, v17, v5
	v_add_u32_e32 v17, v17, v6
	v_add_u32_e32 v17, v17, v7
	v_add_u32_e32 v17, v17, v8
	v_add_u32_e32 v17, v17, v9
	v_add_u32_e32 v17, v17, v10
	v_add_u32_e32 v17, v17, v11
	v_add_u32_e32 v17, v17, v12
	v_add_u32_e32 v17, v17, v13
	v_add_u32_e32 v17, v17, v14
	v_add_u32_e32 v17, v17, v15
	v_add_u32_e32 v17, v17, v16
	v_cmp_ne_u32_e32 vcc, s18, v17
	s_and_saveexec_b64 s[18:19], vcc
	s_cbranch_execz .LBB0_528
	s_and_b32 s22, s28, 0xff
	s_mov_b64 s[20:21], -1
	s_cmp_eq_u32 s22, 0
	s_mov_b64 s[24:25], -1
	s_mov_b64 s[22:23], -1
	s_sleep 0
	s_cbranch_scc1 .LBB0_532
	s_and_saveexec_b64 s[26:27], s[24:25]
	s_cbranch_execz .LBB0_527
	s_branch .LBB0_535

.LBB0_1023:
	v_mov_b64_e32 v[12:13], s[34:35]
	flat_load_dword v2, v[12:13] offset:1024 sc1
	s_waitcnt lgkmcnt(0)
	flat_load_dword v0, v[12:13] offset:1280 sc1
	flat_load_dword v3, v[12:13] offset:1536 sc1
	flat_load_dword v4, v[12:13] offset:1792 sc1
	flat_load_dword v5, v[12:13] offset:2048 sc1
	flat_load_dword v6, v[12:13] offset:2304 sc1
	flat_load_dword v7, v[12:13] offset:2560 sc1
	flat_load_dword v8, v[12:13] offset:2816 sc1
	flat_load_dword v9, v[12:13] offset:3072 sc1
	flat_load_dword v10, v[12:13] offset:3328 sc1
	flat_load_dword v11, v[12:13] offset:3584 sc1
	s_nop 0
	flat_load_dword v12, v[12:13] offset:3840 sc1
	v_mov_b64_e32 v[14:15], s[0:1]
	flat_load_dword v13, v[14:15] sc1
	v_mov_b64_e32 v[14:15], s[2:3]
	flat_load_dword v14, v[14:15] sc1
	v_mov_b64_e32 v[16:17], s[4:5]
	flat_load_dword v15, v[16:17] sc1
	v_mov_b64_e32 v[16:17], s[6:7]
	flat_load_dword v16, v[16:17] sc1
	v_readlane_b32 s16, v254, 12
	s_or_b64 s[14:15], s[14:15], exec
	s_or_b64 s[12:13], s[12:13], exec
	s_waitcnt vmcnt(0) lgkmcnt(0)
	v_add_u32_e32 v17, v0, v2
	v_add_u32_e32 v17, v17, v3
	v_add_u32_e32 v17, v17, v4
	v_add_u32_e32 v17, v17, v5
	v_add_u32_e32 v17, v17, v6
	v_add_u32_e32 v17, v17, v7
	v_add_u32_e32 v17, v17, v8
	v_add_u32_e32 v17, v17, v9
	v_add_u32_e32 v17, v17, v10
	v_add_u32_e32 v17, v17, v11
	v_add_u32_e32 v17, v17, v12
	v_add_u32_e32 v17, v17, v13
	v_add_u32_e32 v17, v17, v14
	v_add_u32_e32 v17, v17, v15
	v_add_u32_e32 v17, v17, v16
	v_cmp_ne_u32_e32 vcc, s16, v17
	s_and_saveexec_b64 s[16:17], vcc
	s_cbranch_execz .LBB0_1022
	s_and_b32 s20, s26, 0xff
	s_mov_b64 s[18:19], -1
	s_cmp_eq_u32 s20, 0
	s_mov_b64 s[22:23], -1
	s_mov_b64 s[20:21], -1
	s_sleep 0
	s_cbranch_scc1 .LBB0_1026
	s_and_saveexec_b64 s[24:25], s[22:23]
	s_cbranch_execz .LBB0_1021
	s_branch .LBB0_1029

.LBB0_1037:
	s_and_b32 s14, s21, 0xff
	s_mov_b64 s[12:13], -1
	s_cmp_lg_u32 s14, 0
	s_mov_b64 s[14:15], -1
	s_sleep 0
	s_cbranch_scc1 .LBB0_1041
	v_mov_b64_e32 v[4:5], s[34:35]
	flat_load_dword v0, v[4:5] offset:512 sc1
	s_mov_b64 s[14:15], 0
	s_mov_b64 s[16:17], -1
	s_waitcnt vmcnt(0) lgkmcnt(0)
	v_cmp_eq_u32_e32 vcc, 0, v0
	s_and_saveexec_b64 s[18:19], vcc
	s_cmp_lt_u32 s21, 0x40001
	s_cselect_b64 s[14:15], -1, 0
	s_xor_b64 s[16:17], exec, -1
	s_and_b64 s[14:15], s[14:15], exec
	s_or_b64 exec, exec, s[18:19]

.LBB0_1051:
	s_and_b32 s14, s21, 0xff
	s_mov_b64 s[12:13], -1
	s_cmp_lg_u32 s14, 0
	s_mov_b64 s[16:17], -1
	s_sleep 0
	s_cbranch_scc0 .LBB0_1053
	s_and_saveexec_b64 s[18:19], s[16:17]
	s_cbranch_execz .LBB0_1050
	s_branch .LBB0_1056
